# group-local seams: L1 invalidate issued before the poll loop (overlaps the wait)
# speedup vs baseline: 1.0180x; 1.0049x over previous
; __device__ __forceinline__ unsigned xb_ld(unsigned* p)              { return __hip_atomic_load(p, __ATOMIC_RELAXED, __HIP_MEMORY_SCOPE_AGENT); }
; __device__ __forceinline__ unsigned xb_add(unsigned* p, unsigned v) { return __hip_atomic_fetch_add(p, v, __ATOMIC_RELAXED, __HIP_MEMORY_SCOPE_AGENT); }
; #define XB_SPIN(cond, bar) do { unsigned _sp = 0; while (cond) { __builtin_amdgcn_s_sleep(1); \
;     if ((++_sp & 255u) == 0u) { if (xb_ld(&(bar)[XB_TMO])) break; if (_sp > XB_SPIN_CAP) { atomicAdd(&(bar)[XB_TMO], 1u); break; } } } } while (0)
; __device__ __forceinline__ void xcd_barrier(const XcdBarrier& b) {
;     asm volatile("s_waitcnt vmcnt(0)" ::: "memory");
;     __syncthreads();
;     if (threadIdx.x == 0) {
;         unsigned* bar = b.bar;
;         __builtin_amdgcn_s_waitcnt(0);
;         unsigned nloc = b.st[0], nx = b.st[1];
;         if (nloc == 0u) { xcd_barrier_complete(bar, b.x, nloc, nx); b.st[0] = nloc; b.st[1] = nx; }
;         const unsigned old = xb_add(&bar[XB_XSUB(b.x)], 1u);
;         const unsigned gen = old / nloc;
;         if (old + 1u == (gen + 1u) * nloc) {
;             __builtin_amdgcn_fence(__ATOMIC_RELEASE, "agent");
;             asm volatile("s_waitcnt vmcnt(0)" ::: "memory");
;             const unsigned og = xb_add(&bar[XB_TOP], 1u);
;             const unsigned tg = og / nx;
;             if (og + 1u == (tg + 1u) * nx) xb_add(&bar[XB_TOPGEN], 1u);
;             else XB_SPIN(xb_ld(&bar[XB_TOPGEN]) == tg, bar);
;             __builtin_amdgcn_fence(__ATOMIC_ACQUIRE, "agent");
;             xb_add(&bar[XB_XGEN(b.x)], 1u);
;             asm volatile("s_waitcnt vmcnt(0)" ::: "memory");
;         } else {
;             XB_SPIN(xb_ld(&bar[XB_XGEN(b.x)]) == gen, bar);
;             __builtin_amdgcn_fence(__ATOMIC_ACQUIRE, "agent");
;             asm volatile("s_waitcnt vmcnt(0)" ::: "memory");
;         }
.LBB9_444:
	v_readlane_b32 s97, v251, 39
	s_cmp_gt_i32 s93, 4
	s_cselect_b64 s[0:1], -1, 0
	s_and_b64 s[2:3], s[22:23], s[0:1]
	s_andn2_b64 vcc, exec, s[2:3]
	s_cbranch_vccnz .LBB9_498
	s_waitcnt vmcnt(0)
	s_waitcnt vmcnt(0) lgkmcnt(0)
	s_barrier
	s_and_saveexec_b64 s[4:5], s[80:81]
	s_cbranch_execz .LBB9_497
	v_mov_b32_e32 v0, 0x24008
	ds_read_b32 v0, v0
	s_waitcnt lgkmcnt(0)
	v_readfirstlane_b32 s98, v0
	s_nop 3
	s_cmp_eq_u32 s98, 1
	s_cbranch_scc0 .Lgb3_orig
	s_cmpk_lg_i32 s94, 0x100
	s_cbranch_scc1 .Lgb3_orig
	s_and_b32 s98, s97, 63
	s_lshl_b32 s98, s98, 2
	s_add_i32 s98, s98, 0x3f00
	v_mov_b32_e32 v0, s98
	v_mov_b32_e32 v1, 1
	global_atomic_add v0, v1, s[90:91]
	buffer_inv sc1
.Lgb3_poll:
	s_sleep 1
	global_load_dword v2, v0, s[90:91] sc1
	s_waitcnt vmcnt(0)
	v_cmp_gt_u32_e32 vcc, 4, v2
	s_cbranch_vccnz .Lgb3_poll
	s_branch .LBB9_497

; __device__ __forceinline__ unsigned xb_ld(unsigned* p)              { return __hip_atomic_load(p, __ATOMIC_RELAXED, __HIP_MEMORY_SCOPE_AGENT); }
; __device__ __forceinline__ unsigned xb_add(unsigned* p, unsigned v) { return __hip_atomic_fetch_add(p, v, __ATOMIC_RELAXED, __HIP_MEMORY_SCOPE_AGENT); }
; #define XB_SPIN(cond, bar) do { unsigned _sp = 0; while (cond) { __builtin_amdgcn_s_sleep(1); \
;     if ((++_sp & 255u) == 0u) { if (xb_ld(&(bar)[XB_TMO])) break; if (_sp > XB_SPIN_CAP) { atomicAdd(&(bar)[XB_TMO], 1u); break; } } } } while (0)
; __device__ __forceinline__ void xcd_barrier(const XcdBarrier& b) {
;     asm volatile("s_waitcnt vmcnt(0)" ::: "memory");
;     __syncthreads();
;     if (threadIdx.x == 0) {
;         unsigned* bar = b.bar;
;         __builtin_amdgcn_s_waitcnt(0);
;         unsigned nloc = b.st[0], nx = b.st[1];
;         if (nloc == 0u) { xcd_barrier_complete(bar, b.x, nloc, nx); b.st[0] = nloc; b.st[1] = nx; }
;         const unsigned old = xb_add(&bar[XB_XSUB(b.x)], 1u);
;         const unsigned gen = old / nloc;
;         if (old + 1u == (gen + 1u) * nloc) {
;             __builtin_amdgcn_fence(__ATOMIC_RELEASE, "agent");
;             asm volatile("s_waitcnt vmcnt(0)" ::: "memory");
;             const unsigned og = xb_add(&bar[XB_TOP], 1u);
;             const unsigned tg = og / nx;
;             if (og + 1u == (tg + 1u) * nx) xb_add(&bar[XB_TOPGEN], 1u);
;             else XB_SPIN(xb_ld(&bar[XB_TOPGEN]) == tg, bar);
;             __builtin_amdgcn_fence(__ATOMIC_ACQUIRE, "agent");
;             xb_add(&bar[XB_XGEN(b.x)], 1u);
;             asm volatile("s_waitcnt vmcnt(0)" ::: "memory");
;         } else {
;             XB_SPIN(xb_ld(&bar[XB_XGEN(b.x)]) == gen, bar);
;             __builtin_amdgcn_fence(__ATOMIC_ACQUIRE, "agent");
;             asm volatile("s_waitcnt vmcnt(0)" ::: "memory");
;         }
.LBB9_591:
	s_cmp_gt_i32 s93, 5
	s_cselect_b64 s[0:1], -1, 0
	s_and_b64 s[2:3], s[6:7], s[0:1]
	s_andn2_b64 vcc, exec, s[2:3]
	s_cbranch_vccnz .LBB9_645
	s_waitcnt vmcnt(0)
	s_waitcnt vmcnt(0) lgkmcnt(0)
	s_barrier
	s_and_saveexec_b64 s[4:5], s[80:81]
	s_cbranch_execz .LBB9_644
	v_mov_b32_e32 v0, 0x24008
	ds_read_b32 v0, v0
	s_waitcnt lgkmcnt(0)
	v_readfirstlane_b32 s98, v0
	s_nop 3
	s_cmp_eq_u32 s98, 1
	s_cbranch_scc0 .Lgb4_orig
	s_and_b32 s98, s97, 63
	s_lshl_b32 s98, s98, 2
	s_add_i32 s98, s98, 0x3d00
	v_mov_b32_e32 v0, s98
	v_mov_b32_e32 v1, 1
	global_atomic_add v0, v1, s[90:91]
	buffer_inv sc1

; __device__ __forceinline__ unsigned xb_ld(unsigned* p)              { return __hip_atomic_load(p, __ATOMIC_RELAXED, __HIP_MEMORY_SCOPE_AGENT); }
; __device__ __forceinline__ unsigned xb_add(unsigned* p, unsigned v) { return __hip_atomic_fetch_add(p, v, __ATOMIC_RELAXED, __HIP_MEMORY_SCOPE_AGENT); }
; #define XB_SPIN(cond, bar) do { unsigned _sp = 0; while (cond) { __builtin_amdgcn_s_sleep(1); \
;     if ((++_sp & 255u) == 0u) { if (xb_ld(&(bar)[XB_TMO])) break; if (_sp > XB_SPIN_CAP) { atomicAdd(&(bar)[XB_TMO], 1u); break; } } } } while (0)
; __device__ __forceinline__ void xcd_barrier(const XcdBarrier& b) {
;     asm volatile("s_waitcnt vmcnt(0)" ::: "memory");
;     __syncthreads();
;     if (threadIdx.x == 0) {
;         unsigned* bar = b.bar;
;         __builtin_amdgcn_s_waitcnt(0);
;         unsigned nloc = b.st[0], nx = b.st[1];
;         if (nloc == 0u) { xcd_barrier_complete(bar, b.x, nloc, nx); b.st[0] = nloc; b.st[1] = nx; }
;         const unsigned old = xb_add(&bar[XB_XSUB(b.x)], 1u);
;         const unsigned gen = old / nloc;
;         if (old + 1u == (gen + 1u) * nloc) {
;             __builtin_amdgcn_fence(__ATOMIC_RELEASE, "agent");
;             asm volatile("s_waitcnt vmcnt(0)" ::: "memory");
;             const unsigned og = xb_add(&bar[XB_TOP], 1u);
;             const unsigned tg = og / nx;
;             if (og + 1u == (tg + 1u) * nx) xb_add(&bar[XB_TOPGEN], 1u);
;             else XB_SPIN(xb_ld(&bar[XB_TOPGEN]) == tg, bar);
;             __builtin_amdgcn_fence(__ATOMIC_ACQUIRE, "agent");
;             xb_add(&bar[XB_XGEN(b.x)], 1u);
;             asm volatile("s_waitcnt vmcnt(0)" ::: "memory");
;         } else {
;             XB_SPIN(xb_ld(&bar[XB_XGEN(b.x)]) == gen, bar);
;             __builtin_amdgcn_fence(__ATOMIC_ACQUIRE, "agent");
;             asm volatile("s_waitcnt vmcnt(0)" ::: "memory");
;         }
.LBB9_777:
	s_cmp_gt_i32 s93, 7
	s_cselect_b64 s[0:1], -1, 0
	s_and_b64 s[2:3], s[4:5], s[0:1]
	s_andn2_b64 vcc, exec, s[2:3]
	s_cbranch_vccnz .LBB9_831
	s_waitcnt vmcnt(0)
	s_waitcnt vmcnt(0) lgkmcnt(0)
	s_barrier
	s_and_saveexec_b64 s[4:5], s[80:81]
	s_cbranch_execz .LBB9_830
	v_mov_b32_e32 v0, 0x24008
	ds_read_b32 v0, v0
	s_waitcnt lgkmcnt(0)
	v_readfirstlane_b32 s98, v0
	s_nop 3
	s_cmp_eq_u32 s98, 1
	s_cbranch_scc0 .Lgb6_orig
	s_and_b32 s98, s97, 63
	s_lshl_b32 s98, s98, 2
	s_add_i32 s98, s98, 0x3e00
	v_mov_b32_e32 v0, s98
	v_mov_b32_e32 v1, 1
	global_atomic_add v0, v1, s[90:91]
	buffer_inv sc1
